# P5 copy-out: gain vector loaded once per item, LDS reads double-buffered, row stores not waited inside the loop
# baseline (speedup 1.0000x reference)
; #define LAS __attribute__((address_space(3)))
; __device__ __forceinline__ void unpack8(u32x4 r, float* f) { f[0] = bflo(r.x); f[1] = bfhi(r.x); f[2] = bflo(r.y); f[3] = bfhi(r.y); f[4] = bflo(r.z); f[5] = bfhi(r.z); f[6] = bflo(r.w); f[7] = bfhi(r.w); }
; __device__ __forceinline__ u32x4 pack8(const float* f) { u32x4 o; o.x = pk2(f[0], f[1]); o.y = pk2(f[2], f[3]); o.z = pk2(f[4], f[5]); o.w = pk2(f[6], f[7]); return o; }
; __device__ __forceinline__ void phase_ssd_y(const PT& p, LAS unsigned char* lds, int tid, int lane, int wave) {
;     ...
;         __syncthreads();
;         if (pb == 0 && h == 0) rsT[l] = rsqrtf((ssqp[l] + ssqp[128 + l]) * (1.f / 512.f) + EPS);
;         __syncthreads();
; #pragma unroll 4
;         for (int i = 0; i < 16; ++i) { const int pid = tid + 512 * i, row = pid >> 6, c8 = pid & 63; const int ch = grp * 512 + 8 * c8;
;             float f[8]; unpack8(*(const LAS u32x4*)(tile + row * SY_TP + 16 * c8), f);
;             const float rs = rsT[row]; const f32x4 g0 = *(const f32x4*)(p.in[12] + ch), g1 = *(const f32x4*)(p.in[12] + ch + 4);
;             f[0] *= rs * g0.x; f[1] *= rs * g0.y; f[2] *= rs * g0.z; f[3] *= rs * g0.w; f[4] *= rs * g1.x; f[5] *= rs * g1.y; f[6] *= rs * g1.z; f[7] *= rs * g1.w;
;             *(u32x4*)(Ycat + ((size_t)tok0 + row) * 4096 + 2048 + ch) = pack8(f); }
.LBB0_511:
	s_or_b64 exec, exec, s[2:3]
	s_waitcnt lgkmcnt(0)
	s_barrier
	ds_read_b64 v[0:1], v191
	v_or_b32_e32 v2, s1, v118
	s_mov_b32 s1, 0
	v_lshlrev_b32_e32 v6, 2, v2
	v_lshlrev_b32_e32 v3, 1, v2
	v_ashrrev_i32_e32 v4, 6, v117
	v_mul_u32_u24_e32 v7, 0x410, v4
	v_add_u32_e32 v7, v7, v122
	v_lshlrev_b32_e32 v5, 2, v4
	s_waitcnt lgkmcnt(0)
	v_readfirstlane_b32 s3, v1
	v_readfirstlane_b32 s2, v0
	v_readfirstlane_b32 s98, v117
	s_lshr_b32 s98, s98, 6
	s_add_u32 s98, s98, s92
	s_addc_u32 s99, s93, 0
	s_lshl_b64 s[98:99], s[98:99], 13
	s_add_u32 s98, s98, s88
	s_addc_u32 s99, s99, s89
	s_add_u32 s98, s98, 0x1000
	s_addc_u32 s99, s99, 0
	global_load_dwordx4 v[12:15], v6, s[2:3] offset:16
	global_load_dwordx4 v[16:19], v6, s[2:3]
	ds_read_b128 v[24:27], v7 offset:9728
	ds_read_b32 v32, v5 offset:9216
	v_add_u32_e32 v7, 0x2080, v7
	ds_read_b128 v[28:31], v7 offset:9728
	ds_read_b32 v33, v5 offset:9248
	s_waitcnt lgkmcnt(2)
	s_waitcnt vmcnt(0)
	v_lshlrev_b32_e32 v34, 16, v24
	v_and_b32_e32 v35, 0xffff0000, v24
	v_lshlrev_b32_e32 v36, 16, v25
	v_and_b32_e32 v37, 0xffff0000, v25
	v_lshlrev_b32_e32 v38, 16, v26
	v_and_b32_e32 v39, 0xffff0000, v26
	v_lshlrev_b32_e32 v40, 16, v27
	v_and_b32_e32 v41, 0xffff0000, v27
	v_mul_f32_e32 v42, v32, v16
	v_mul_f32_e32 v43, v32, v17
	v_mul_f32_e32 v44, v32, v18
	v_mul_f32_e32 v45, v32, v19
	v_mul_f32_e32 v46, v32, v12
	v_mul_f32_e32 v47, v32, v13
	v_mul_f32_e32 v48, v32, v14
	v_mul_f32_e32 v49, v32, v15
	v_mul_f32_e32 v42, v42, v34
	v_mul_f32_e32 v43, v43, v35
	v_mul_f32_e32 v44, v44, v36
	v_mul_f32_e32 v45, v45, v37
	v_mul_f32_e32 v46, v46, v38
	v_mul_f32_e32 v47, v47, v39
	v_mul_f32_e32 v48, v48, v40
	v_mul_f32_e32 v49, v49, v41
	v_cvt_pk_bf16_f32 v50, v42, v43
	v_cvt_pk_bf16_f32 v51, v44, v45
	v_cvt_pk_bf16_f32 v52, v46, v47
	v_cvt_pk_bf16_f32 v53, v48, v49
	global_store_dwordx4 v3, v[50:53], s[98:99]
	s_add_u32 s98, s98, 0x10000
	s_addc_u32 s99, s99, 0
	v_add_u32_e32 v7, 0x2080, v7
	ds_read_b128 v[24:27], v7 offset:9728
	ds_read_b32 v32, v5 offset:9280
	s_waitcnt lgkmcnt(2)
	v_lshlrev_b32_e32 v34, 16, v28
	v_and_b32_e32 v35, 0xffff0000, v28
	v_lshlrev_b32_e32 v36, 16, v29
	v_and_b32_e32 v37, 0xffff0000, v29
	v_lshlrev_b32_e32 v38, 16, v30
	v_and_b32_e32 v39, 0xffff0000, v30
	v_lshlrev_b32_e32 v40, 16, v31
	v_and_b32_e32 v41, 0xffff0000, v31
	v_mul_f32_e32 v42, v33, v16
	v_mul_f32_e32 v43, v33, v17
	v_mul_f32_e32 v44, v33, v18
	v_mul_f32_e32 v45, v33, v19
	v_mul_f32_e32 v46, v33, v12
	v_mul_f32_e32 v47, v33, v13
	v_mul_f32_e32 v48, v33, v14
	v_mul_f32_e32 v49, v33, v15
	v_mul_f32_e32 v42, v42, v34
	v_mul_f32_e32 v43, v43, v35
	v_mul_f32_e32 v44, v44, v36
	v_mul_f32_e32 v45, v45, v37
	v_mul_f32_e32 v46, v46, v38
	v_mul_f32_e32 v47, v47, v39
	v_mul_f32_e32 v48, v48, v40
	v_mul_f32_e32 v49, v49, v41
	v_cvt_pk_bf16_f32 v54, v42, v43
	v_cvt_pk_bf16_f32 v55, v44, v45
	v_cvt_pk_bf16_f32 v56, v46, v47
	v_cvt_pk_bf16_f32 v57, v48, v49
	global_store_dwordx4 v3, v[54:57], s[98:99]
	s_add_u32 s98, s98, 0x10000
	s_addc_u32 s99, s99, 0
	v_add_u32_e32 v7, 0x2080, v7
	ds_read_b128 v[28:31], v7 offset:9728
	ds_read_b32 v33, v5 offset:9312
	s_waitcnt lgkmcnt(2)
	v_lshlrev_b32_e32 v34, 16, v24
	v_and_b32_e32 v35, 0xffff0000, v24
	v_lshlrev_b32_e32 v36, 16, v25
	v_and_b32_e32 v37, 0xffff0000, v25
	v_lshlrev_b32_e32 v38, 16, v26
	v_and_b32_e32 v39, 0xffff0000, v26
	v_lshlrev_b32_e32 v40, 16, v27
	v_and_b32_e32 v41, 0xffff0000, v27
	v_mul_f32_e32 v42, v32, v16
	v_mul_f32_e32 v43, v32, v17
	v_mul_f32_e32 v44, v32, v18
	v_mul_f32_e32 v45, v32, v19
	v_mul_f32_e32 v46, v32, v12
	v_mul_f32_e32 v47, v32, v13
	v_mul_f32_e32 v48, v32, v14
	v_mul_f32_e32 v49, v32, v15
	v_mul_f32_e32 v42, v42, v34
	v_mul_f32_e32 v43, v43, v35
	v_mul_f32_e32 v44, v44, v36
	v_mul_f32_e32 v45, v45, v37
	v_mul_f32_e32 v46, v46, v38
	v_mul_f32_e32 v47, v47, v39
	v_mul_f32_e32 v48, v48, v40
	v_mul_f32_e32 v49, v49, v41
	v_cvt_pk_bf16_f32 v50, v42, v43
	v_cvt_pk_bf16_f32 v51, v44, v45
	v_cvt_pk_bf16_f32 v52, v46, v47
	v_cvt_pk_bf16_f32 v53, v48, v49
	global_store_dwordx4 v3, v[50:53], s[98:99]
	s_add_u32 s98, s98, 0x10000
	s_addc_u32 s99, s99, 0
	v_add_u32_e32 v7, 0x2080, v7
	ds_read_b128 v[24:27], v7 offset:9728
	ds_read_b32 v32, v5 offset:9344
	s_waitcnt lgkmcnt(2)
	v_lshlrev_b32_e32 v34, 16, v28
	v_and_b32_e32 v35, 0xffff0000, v28
	v_lshlrev_b32_e32 v36, 16, v29
	v_and_b32_e32 v37, 0xffff0000, v29
	v_lshlrev_b32_e32 v38, 16, v30
	v_and_b32_e32 v39, 0xffff0000, v30
	v_lshlrev_b32_e32 v40, 16, v31
	v_and_b32_e32 v41, 0xffff0000, v31
	v_mul_f32_e32 v42, v33, v16
	v_mul_f32_e32 v43, v33, v17
	v_mul_f32_e32 v44, v33, v18
	v_mul_f32_e32 v45, v33, v19
	v_mul_f32_e32 v46, v33, v12
	v_mul_f32_e32 v47, v33, v13
	v_mul_f32_e32 v48, v33, v14
	v_mul_f32_e32 v49, v33, v15
	v_mul_f32_e32 v42, v42, v34
	v_mul_f32_e32 v43, v43, v35
	v_mul_f32_e32 v44, v44, v36
	v_mul_f32_e32 v45, v45, v37
	v_mul_f32_e32 v46, v46, v38
	v_mul_f32_e32 v47, v47, v39
	v_mul_f32_e32 v48, v48, v40
	v_mul_f32_e32 v49, v49, v41
	v_cvt_pk_bf16_f32 v54, v42, v43
	v_cvt_pk_bf16_f32 v55, v44, v45
	v_cvt_pk_bf16_f32 v56, v46, v47
	v_cvt_pk_bf16_f32 v57, v48, v49
	global_store_dwordx4 v3, v[54:57], s[98:99]
	s_add_u32 s98, s98, 0x10000
	s_addc_u32 s99, s99, 0
	v_add_u32_e32 v7, 0x2080, v7
	ds_read_b128 v[28:31], v7 offset:9728
	ds_read_b32 v33, v5 offset:9376
	s_waitcnt lgkmcnt(2)
; #define LAS __attribute__((address_space(3)))
; __device__ __forceinline__ void unpack8(u32x4 r, float* f) { f[0] = bflo(r.x); f[1] = bfhi(r.x); f[2] = bflo(r.y); f[3] = bfhi(r.y); f[4] = bflo(r.z); f[5] = bfhi(r.z); f[6] = bflo(r.w); f[7] = bfhi(r.w); }
; __device__ __forceinline__ u32x4 pack8(const float* f) { u32x4 o; o.x = pk2(f[0], f[1]); o.y = pk2(f[2], f[3]); o.z = pk2(f[4], f[5]); o.w = pk2(f[6], f[7]); return o; }
; __device__ __forceinline__ void phase_ssd_y(const PT& p, LAS unsigned char* lds, int tid, int lane, int wave) {
;     ...
; #pragma unroll 4
;         for (int i = 0; i < 16; ++i) { const int pid = tid + 512 * i, row = pid >> 6, c8 = pid & 63; const int ch = grp * 512 + 8 * c8;
;             float f[8]; unpack8(*(const LAS u32x4*)(tile + row * SY_TP + 16 * c8), f);
;             const float rs = rsT[row]; const f32x4 g0 = *(const f32x4*)(p.in[12] + ch), g1 = *(const f32x4*)(p.in[12] + ch + 4);
;             f[0] *= rs * g0.x; f[1] *= rs * g0.y; f[2] *= rs * g0.z; f[3] *= rs * g0.w; f[4] *= rs * g1.x; f[5] *= rs * g1.y; f[6] *= rs * g1.z; f[7] *= rs * g1.w;
;             *(u32x4*)(Ycat + ((size_t)tok0 + row) * 4096 + 2048 + ch) = pack8(f); }
	v_lshlrev_b32_e32 v34, 16, v24
	v_and_b32_e32 v35, 0xffff0000, v24
	v_lshlrev_b32_e32 v36, 16, v25
	v_and_b32_e32 v37, 0xffff0000, v25
	v_lshlrev_b32_e32 v38, 16, v26
	v_and_b32_e32 v39, 0xffff0000, v26
	v_lshlrev_b32_e32 v40, 16, v27
	v_and_b32_e32 v41, 0xffff0000, v27
	v_mul_f32_e32 v42, v32, v16
	v_mul_f32_e32 v43, v32, v17
	v_mul_f32_e32 v44, v32, v18
	v_mul_f32_e32 v45, v32, v19
	v_mul_f32_e32 v46, v32, v12
	v_mul_f32_e32 v47, v32, v13
	v_mul_f32_e32 v48, v32, v14
	v_mul_f32_e32 v49, v32, v15
	v_mul_f32_e32 v42, v42, v34
	v_mul_f32_e32 v43, v43, v35
	v_mul_f32_e32 v44, v44, v36
	v_mul_f32_e32 v45, v45, v37
	v_mul_f32_e32 v46, v46, v38
	v_mul_f32_e32 v47, v47, v39
	v_mul_f32_e32 v48, v48, v40
	v_mul_f32_e32 v49, v49, v41
	v_cvt_pk_bf16_f32 v50, v42, v43
	v_cvt_pk_bf16_f32 v51, v44, v45
	v_cvt_pk_bf16_f32 v52, v46, v47
	v_cvt_pk_bf16_f32 v53, v48, v49
	global_store_dwordx4 v3, v[50:53], s[98:99]
	s_add_u32 s98, s98, 0x10000
	s_addc_u32 s99, s99, 0
	v_add_u32_e32 v7, 0x2080, v7
	ds_read_b128 v[24:27], v7 offset:9728
	ds_read_b32 v32, v5 offset:9408
	s_waitcnt lgkmcnt(2)
	v_lshlrev_b32_e32 v34, 16, v28
	v_and_b32_e32 v35, 0xffff0000, v28
	v_lshlrev_b32_e32 v36, 16, v29
	v_and_b32_e32 v37, 0xffff0000, v29
	v_lshlrev_b32_e32 v38, 16, v30
	v_and_b32_e32 v39, 0xffff0000, v30
	v_lshlrev_b32_e32 v40, 16, v31
	v_and_b32_e32 v41, 0xffff0000, v31
	v_mul_f32_e32 v42, v33, v16
	v_mul_f32_e32 v43, v33, v17
	v_mul_f32_e32 v44, v33, v18
	v_mul_f32_e32 v45, v33, v19
	v_mul_f32_e32 v46, v33, v12
	v_mul_f32_e32 v47, v33, v13
	v_mul_f32_e32 v48, v33, v14
	v_mul_f32_e32 v49, v33, v15
	v_mul_f32_e32 v42, v42, v34
	v_mul_f32_e32 v43, v43, v35
	v_mul_f32_e32 v44, v44, v36
	v_mul_f32_e32 v45, v45, v37
	v_mul_f32_e32 v46, v46, v38
	v_mul_f32_e32 v47, v47, v39
	v_mul_f32_e32 v48, v48, v40
	v_mul_f32_e32 v49, v49, v41
	v_cvt_pk_bf16_f32 v54, v42, v43
	v_cvt_pk_bf16_f32 v55, v44, v45
	v_cvt_pk_bf16_f32 v56, v46, v47
	v_cvt_pk_bf16_f32 v57, v48, v49
	global_store_dwordx4 v3, v[54:57], s[98:99]
	s_add_u32 s98, s98, 0x10000
	s_addc_u32 s99, s99, 0
	v_add_u32_e32 v7, 0x2080, v7
	ds_read_b128 v[28:31], v7 offset:9728
	ds_read_b32 v33, v5 offset:9440
	s_waitcnt lgkmcnt(2)
	v_lshlrev_b32_e32 v34, 16, v24
	v_and_b32_e32 v35, 0xffff0000, v24
	v_lshlrev_b32_e32 v36, 16, v25
	v_and_b32_e32 v37, 0xffff0000, v25
	v_lshlrev_b32_e32 v38, 16, v26
	v_and_b32_e32 v39, 0xffff0000, v26
	v_lshlrev_b32_e32 v40, 16, v27
	v_and_b32_e32 v41, 0xffff0000, v27
	v_mul_f32_e32 v42, v32, v16
	v_mul_f32_e32 v43, v32, v17
	v_mul_f32_e32 v44, v32, v18
	v_mul_f32_e32 v45, v32, v19
	v_mul_f32_e32 v46, v32, v12
	v_mul_f32_e32 v47, v32, v13
	v_mul_f32_e32 v48, v32, v14
	v_mul_f32_e32 v49, v32, v15
	v_mul_f32_e32 v42, v42, v34
	v_mul_f32_e32 v43, v43, v35
	v_mul_f32_e32 v44, v44, v36
	v_mul_f32_e32 v45, v45, v37
	v_mul_f32_e32 v46, v46, v38
	v_mul_f32_e32 v47, v47, v39
	v_mul_f32_e32 v48, v48, v40
	v_mul_f32_e32 v49, v49, v41
	v_cvt_pk_bf16_f32 v50, v42, v43
	v_cvt_pk_bf16_f32 v51, v44, v45
	v_cvt_pk_bf16_f32 v52, v46, v47
	v_cvt_pk_bf16_f32 v53, v48, v49
	global_store_dwordx4 v3, v[50:53], s[98:99]
	s_add_u32 s98, s98, 0x10000
	s_addc_u32 s99, s99, 0
	v_add_u32_e32 v7, 0x2080, v7
	ds_read_b128 v[24:27], v7 offset:9728
	ds_read_b32 v32, v5 offset:9472
	s_waitcnt lgkmcnt(2)
	v_lshlrev_b32_e32 v34, 16, v28
	v_and_b32_e32 v35, 0xffff0000, v28
	v_lshlrev_b32_e32 v36, 16, v29
	v_and_b32_e32 v37, 0xffff0000, v29
	v_lshlrev_b32_e32 v38, 16, v30
	v_and_b32_e32 v39, 0xffff0000, v30
	v_lshlrev_b32_e32 v40, 16, v31
	v_and_b32_e32 v41, 0xffff0000, v31
	v_mul_f32_e32 v42, v33, v16
	v_mul_f32_e32 v43, v33, v17
	v_mul_f32_e32 v44, v33, v18
	v_mul_f32_e32 v45, v33, v19
	v_mul_f32_e32 v46, v33, v12
	v_mul_f32_e32 v47, v33, v13
	v_mul_f32_e32 v48, v33, v14
	v_mul_f32_e32 v49, v33, v15
	v_mul_f32_e32 v42, v42, v34
	v_mul_f32_e32 v43, v43, v35
	v_mul_f32_e32 v44, v44, v36
	v_mul_f32_e32 v45, v45, v37
	v_mul_f32_e32 v46, v46, v38
	v_mul_f32_e32 v47, v47, v39
	v_mul_f32_e32 v48, v48, v40
	v_mul_f32_e32 v49, v49, v41
	v_cvt_pk_bf16_f32 v54, v42, v43
	v_cvt_pk_bf16_f32 v55, v44, v45
	v_cvt_pk_bf16_f32 v56, v46, v47
	v_cvt_pk_bf16_f32 v57, v48, v49
	global_store_dwordx4 v3, v[54:57], s[98:99]
	s_add_u32 s98, s98, 0x10000
	s_addc_u32 s99, s99, 0
	v_add_u32_e32 v7, 0x2080, v7
	ds_read_b128 v[28:31], v7 offset:9728
	ds_read_b32 v33, v5 offset:9504
	s_waitcnt lgkmcnt(2)
	v_lshlrev_b32_e32 v34, 16, v24
	v_and_b32_e32 v35, 0xffff0000, v24
	v_lshlrev_b32_e32 v36, 16, v25
	v_and_b32_e32 v37, 0xffff0000, v25
	v_lshlrev_b32_e32 v38, 16, v26
	v_and_b32_e32 v39, 0xffff0000, v26
	v_lshlrev_b32_e32 v40, 16, v27
	v_and_b32_e32 v41, 0xffff0000, v27
	v_mul_f32_e32 v42, v32, v16
	v_mul_f32_e32 v43, v32, v17
	v_mul_f32_e32 v44, v32, v18
	v_mul_f32_e32 v45, v32, v19
	v_mul_f32_e32 v46, v32, v12
	v_mul_f32_e32 v47, v32, v13
	v_mul_f32_e32 v48, v32, v14
	v_mul_f32_e32 v49, v32, v15
	v_mul_f32_e32 v42, v42, v34
	v_mul_f32_e32 v43, v43, v35
	v_mul_f32_e32 v44, v44, v36
	v_mul_f32_e32 v45, v45, v37
	v_mul_f32_e32 v46, v46, v38
	v_mul_f32_e32 v47, v47, v39
	v_mul_f32_e32 v48, v48, v40
	v_mul_f32_e32 v49, v49, v41
	v_cvt_pk_bf16_f32 v50, v42, v43
	v_cvt_pk_bf16_f32 v51, v44, v45
	v_cvt_pk_bf16_f32 v52, v46, v47
	v_cvt_pk_bf16_f32 v53, v48, v49
	global_store_dwordx4 v3, v[50:53], s[98:99]
	s_add_u32 s98, s98, 0x10000
	s_addc_u32 s99, s99, 0
	v_add_u32_e32 v7, 0x2080, v7
	ds_read_b128 v[24:27], v7 offset:9728
	ds_read_b32 v32, v5 offset:9536
	s_waitcnt lgkmcnt(2)
; #define LAS __attribute__((address_space(3)))
; __device__ __forceinline__ void unpack8(u32x4 r, float* f) { f[0] = bflo(r.x); f[1] = bfhi(r.x); f[2] = bflo(r.y); f[3] = bfhi(r.y); f[4] = bflo(r.z); f[5] = bfhi(r.z); f[6] = bflo(r.w); f[7] = bfhi(r.w); }
; __device__ __forceinline__ u32x4 pack8(const float* f) { u32x4 o; o.x = pk2(f[0], f[1]); o.y = pk2(f[2], f[3]); o.z = pk2(f[4], f[5]); o.w = pk2(f[6], f[7]); return o; }
; __device__ __forceinline__ void phase_ssd_y(const PT& p, LAS unsigned char* lds, int tid, int lane, int wave) {
;     ...
; #pragma unroll 4
;         for (int i = 0; i < 16; ++i) { const int pid = tid + 512 * i, row = pid >> 6, c8 = pid & 63; const int ch = grp * 512 + 8 * c8;
;             float f[8]; unpack8(*(const LAS u32x4*)(tile + row * SY_TP + 16 * c8), f);
;             const float rs = rsT[row]; const f32x4 g0 = *(const f32x4*)(p.in[12] + ch), g1 = *(const f32x4*)(p.in[12] + ch + 4);
;             f[0] *= rs * g0.x; f[1] *= rs * g0.y; f[2] *= rs * g0.z; f[3] *= rs * g0.w; f[4] *= rs * g1.x; f[5] *= rs * g1.y; f[6] *= rs * g1.z; f[7] *= rs * g1.w;
;             *(u32x4*)(Ycat + ((size_t)tok0 + row) * 4096 + 2048 + ch) = pack8(f); }
	v_lshlrev_b32_e32 v34, 16, v28
	v_and_b32_e32 v35, 0xffff0000, v28
	v_lshlrev_b32_e32 v36, 16, v29
	v_and_b32_e32 v37, 0xffff0000, v29
	v_lshlrev_b32_e32 v38, 16, v30
	v_and_b32_e32 v39, 0xffff0000, v30
	v_lshlrev_b32_e32 v40, 16, v31
	v_and_b32_e32 v41, 0xffff0000, v31
	v_mul_f32_e32 v42, v33, v16
	v_mul_f32_e32 v43, v33, v17
	v_mul_f32_e32 v44, v33, v18
	v_mul_f32_e32 v45, v33, v19
	v_mul_f32_e32 v46, v33, v12
	v_mul_f32_e32 v47, v33, v13
	v_mul_f32_e32 v48, v33, v14
	v_mul_f32_e32 v49, v33, v15
	v_mul_f32_e32 v42, v42, v34
	v_mul_f32_e32 v43, v43, v35
	v_mul_f32_e32 v44, v44, v36
	v_mul_f32_e32 v45, v45, v37
	v_mul_f32_e32 v46, v46, v38
	v_mul_f32_e32 v47, v47, v39
	v_mul_f32_e32 v48, v48, v40
	v_mul_f32_e32 v49, v49, v41
	v_cvt_pk_bf16_f32 v54, v42, v43
	v_cvt_pk_bf16_f32 v55, v44, v45
	v_cvt_pk_bf16_f32 v56, v46, v47
	v_cvt_pk_bf16_f32 v57, v48, v49
	global_store_dwordx4 v3, v[54:57], s[98:99]
	s_add_u32 s98, s98, 0x10000
	s_addc_u32 s99, s99, 0
	v_add_u32_e32 v7, 0x2080, v7
	ds_read_b128 v[28:31], v7 offset:9728
	ds_read_b32 v33, v5 offset:9568
	s_waitcnt lgkmcnt(2)
	v_lshlrev_b32_e32 v34, 16, v24
	v_and_b32_e32 v35, 0xffff0000, v24
	v_lshlrev_b32_e32 v36, 16, v25
	v_and_b32_e32 v37, 0xffff0000, v25
	v_lshlrev_b32_e32 v38, 16, v26
	v_and_b32_e32 v39, 0xffff0000, v26
	v_lshlrev_b32_e32 v40, 16, v27
	v_and_b32_e32 v41, 0xffff0000, v27
	v_mul_f32_e32 v42, v32, v16
	v_mul_f32_e32 v43, v32, v17
	v_mul_f32_e32 v44, v32, v18
	v_mul_f32_e32 v45, v32, v19
	v_mul_f32_e32 v46, v32, v12
	v_mul_f32_e32 v47, v32, v13
	v_mul_f32_e32 v48, v32, v14
	v_mul_f32_e32 v49, v32, v15
	v_mul_f32_e32 v42, v42, v34
	v_mul_f32_e32 v43, v43, v35
	v_mul_f32_e32 v44, v44, v36
	v_mul_f32_e32 v45, v45, v37
	v_mul_f32_e32 v46, v46, v38
	v_mul_f32_e32 v47, v47, v39
	v_mul_f32_e32 v48, v48, v40
	v_mul_f32_e32 v49, v49, v41
	v_cvt_pk_bf16_f32 v50, v42, v43
	v_cvt_pk_bf16_f32 v51, v44, v45
	v_cvt_pk_bf16_f32 v52, v46, v47
	v_cvt_pk_bf16_f32 v53, v48, v49
	global_store_dwordx4 v3, v[50:53], s[98:99]
	s_add_u32 s98, s98, 0x10000
	s_addc_u32 s99, s99, 0
	v_add_u32_e32 v7, 0x2080, v7
	ds_read_b128 v[24:27], v7 offset:9728
	ds_read_b32 v32, v5 offset:9600
	s_waitcnt lgkmcnt(2)
	v_lshlrev_b32_e32 v34, 16, v28
	v_and_b32_e32 v35, 0xffff0000, v28
	v_lshlrev_b32_e32 v36, 16, v29
	v_and_b32_e32 v37, 0xffff0000, v29
	v_lshlrev_b32_e32 v38, 16, v30
	v_and_b32_e32 v39, 0xffff0000, v30
	v_lshlrev_b32_e32 v40, 16, v31
	v_and_b32_e32 v41, 0xffff0000, v31
	v_mul_f32_e32 v42, v33, v16
	v_mul_f32_e32 v43, v33, v17
	v_mul_f32_e32 v44, v33, v18
	v_mul_f32_e32 v45, v33, v19
	v_mul_f32_e32 v46, v33, v12
	v_mul_f32_e32 v47, v33, v13
	v_mul_f32_e32 v48, v33, v14
	v_mul_f32_e32 v49, v33, v15
	v_mul_f32_e32 v42, v42, v34
	v_mul_f32_e32 v43, v43, v35
	v_mul_f32_e32 v44, v44, v36
	v_mul_f32_e32 v45, v45, v37
	v_mul_f32_e32 v46, v46, v38
	v_mul_f32_e32 v47, v47, v39
	v_mul_f32_e32 v48, v48, v40
	v_mul_f32_e32 v49, v49, v41
	v_cvt_pk_bf16_f32 v54, v42, v43
	v_cvt_pk_bf16_f32 v55, v44, v45
	v_cvt_pk_bf16_f32 v56, v46, v47
	v_cvt_pk_bf16_f32 v57, v48, v49
	global_store_dwordx4 v3, v[54:57], s[98:99]
	s_add_u32 s98, s98, 0x10000
	s_addc_u32 s99, s99, 0
	v_add_u32_e32 v7, 0x2080, v7
	ds_read_b128 v[28:31], v7 offset:9728
	ds_read_b32 v33, v5 offset:9632
	s_waitcnt lgkmcnt(2)
	v_lshlrev_b32_e32 v34, 16, v24
	v_and_b32_e32 v35, 0xffff0000, v24
	v_lshlrev_b32_e32 v36, 16, v25
	v_and_b32_e32 v37, 0xffff0000, v25
	v_lshlrev_b32_e32 v38, 16, v26
	v_and_b32_e32 v39, 0xffff0000, v26
	v_lshlrev_b32_e32 v40, 16, v27
	v_and_b32_e32 v41, 0xffff0000, v27
	v_mul_f32_e32 v42, v32, v16
	v_mul_f32_e32 v43, v32, v17
	v_mul_f32_e32 v44, v32, v18
	v_mul_f32_e32 v45, v32, v19
	v_mul_f32_e32 v46, v32, v12
	v_mul_f32_e32 v47, v32, v13
	v_mul_f32_e32 v48, v32, v14
	v_mul_f32_e32 v49, v32, v15
	v_mul_f32_e32 v42, v42, v34
	v_mul_f32_e32 v43, v43, v35
	v_mul_f32_e32 v44, v44, v36
	v_mul_f32_e32 v45, v45, v37
	v_mul_f32_e32 v46, v46, v38
	v_mul_f32_e32 v47, v47, v39
	v_mul_f32_e32 v48, v48, v40
	v_mul_f32_e32 v49, v49, v41
	v_cvt_pk_bf16_f32 v50, v42, v43
	v_cvt_pk_bf16_f32 v51, v44, v45
	v_cvt_pk_bf16_f32 v52, v46, v47
	v_cvt_pk_bf16_f32 v53, v48, v49
	global_store_dwordx4 v3, v[50:53], s[98:99]
	s_add_u32 s98, s98, 0x10000
	s_addc_u32 s99, s99, 0
	v_add_u32_e32 v7, 0x2080, v7
	ds_read_b128 v[24:27], v7 offset:9728
	ds_read_b32 v32, v5 offset:9664
	s_waitcnt lgkmcnt(2)
; #define LAS __attribute__((address_space(3)))
; __device__ __forceinline__ void unpack8(u32x4 r, float* f) { f[0] = bflo(r.x); f[1] = bfhi(r.x); f[2] = bflo(r.y); f[3] = bfhi(r.y); f[4] = bflo(r.z); f[5] = bfhi(r.z); f[6] = bflo(r.w); f[7] = bfhi(r.w); }
; __device__ __forceinline__ u32x4 pack8(const float* f) { u32x4 o; o.x = pk2(f[0], f[1]); o.y = pk2(f[2], f[3]); o.z = pk2(f[4], f[5]); o.w = pk2(f[6], f[7]); return o; }
; __device__ __forceinline__ void phase_ssd_y(const PT& p, LAS unsigned char* lds, int tid, int lane, int wave) {
;     ...
;     for (int it = blockIdx.x; it < 128 * 4; it += gridDim.x) {
;     ...
; #pragma unroll 4
;         for (int i = 0; i < 16; ++i) { const int pid = tid + 512 * i, row = pid >> 6, c8 = pid & 63; const int ch = grp * 512 + 8 * c8;
;             float f[8]; unpack8(*(const LAS u32x4*)(tile + row * SY_TP + 16 * c8), f);
;             const float rs = rsT[row]; const f32x4 g0 = *(const f32x4*)(p.in[12] + ch), g1 = *(const f32x4*)(p.in[12] + ch + 4);
;             f[0] *= rs * g0.x; f[1] *= rs * g0.y; f[2] *= rs * g0.z; f[3] *= rs * g0.w; f[4] *= rs * g1.x; f[5] *= rs * g1.y; f[6] *= rs * g1.z; f[7] *= rs * g1.w;
;             *(u32x4*)(Ycat + ((size_t)tok0 + row) * 4096 + 2048 + ch) = pack8(f); }
	v_lshlrev_b32_e32 v34, 16, v28
	v_and_b32_e32 v35, 0xffff0000, v28
	v_lshlrev_b32_e32 v36, 16, v29
	v_and_b32_e32 v37, 0xffff0000, v29
	v_lshlrev_b32_e32 v38, 16, v30
	v_and_b32_e32 v39, 0xffff0000, v30
	v_lshlrev_b32_e32 v40, 16, v31
	v_and_b32_e32 v41, 0xffff0000, v31
	v_mul_f32_e32 v42, v33, v16
	v_mul_f32_e32 v43, v33, v17
	v_mul_f32_e32 v44, v33, v18
	v_mul_f32_e32 v45, v33, v19
	v_mul_f32_e32 v46, v33, v12
	v_mul_f32_e32 v47, v33, v13
	v_mul_f32_e32 v48, v33, v14
	v_mul_f32_e32 v49, v33, v15
	v_mul_f32_e32 v42, v42, v34
	v_mul_f32_e32 v43, v43, v35
	v_mul_f32_e32 v44, v44, v36
	v_mul_f32_e32 v45, v45, v37
	v_mul_f32_e32 v46, v46, v38
	v_mul_f32_e32 v47, v47, v39
	v_mul_f32_e32 v48, v48, v40
	v_mul_f32_e32 v49, v49, v41
	v_cvt_pk_bf16_f32 v54, v42, v43
	v_cvt_pk_bf16_f32 v55, v44, v45
	v_cvt_pk_bf16_f32 v56, v46, v47
	v_cvt_pk_bf16_f32 v57, v48, v49
	global_store_dwordx4 v3, v[54:57], s[98:99]
	s_add_u32 s98, s98, 0x10000
	s_addc_u32 s99, s99, 0
	v_add_u32_e32 v7, 0x2080, v7
	ds_read_b128 v[28:31], v7 offset:9728
	ds_read_b32 v33, v5 offset:9696
	s_waitcnt lgkmcnt(2)
	v_lshlrev_b32_e32 v34, 16, v24
	v_and_b32_e32 v35, 0xffff0000, v24
	v_lshlrev_b32_e32 v36, 16, v25
	v_and_b32_e32 v37, 0xffff0000, v25
	v_lshlrev_b32_e32 v38, 16, v26
	v_and_b32_e32 v39, 0xffff0000, v26
	v_lshlrev_b32_e32 v40, 16, v27
	v_and_b32_e32 v41, 0xffff0000, v27
	v_mul_f32_e32 v42, v32, v16
	v_mul_f32_e32 v43, v32, v17
	v_mul_f32_e32 v44, v32, v18
	v_mul_f32_e32 v45, v32, v19
	v_mul_f32_e32 v46, v32, v12
	v_mul_f32_e32 v47, v32, v13
	v_mul_f32_e32 v48, v32, v14
	v_mul_f32_e32 v49, v32, v15
	v_mul_f32_e32 v42, v42, v34
	v_mul_f32_e32 v43, v43, v35
	v_mul_f32_e32 v44, v44, v36
	v_mul_f32_e32 v45, v45, v37
	v_mul_f32_e32 v46, v46, v38
	v_mul_f32_e32 v47, v47, v39
	v_mul_f32_e32 v48, v48, v40
	v_mul_f32_e32 v49, v49, v41
	v_cvt_pk_bf16_f32 v50, v42, v43
	v_cvt_pk_bf16_f32 v51, v44, v45
	v_cvt_pk_bf16_f32 v52, v46, v47
	v_cvt_pk_bf16_f32 v53, v48, v49
	global_store_dwordx4 v3, v[50:53], s[98:99]
	s_add_u32 s98, s98, 0x10000
	s_addc_u32 s99, s99, 0
	s_waitcnt lgkmcnt(0)
	v_lshlrev_b32_e32 v34, 16, v28
	v_and_b32_e32 v35, 0xffff0000, v28
	v_lshlrev_b32_e32 v36, 16, v29
	v_and_b32_e32 v37, 0xffff0000, v29
	v_lshlrev_b32_e32 v38, 16, v30
	v_and_b32_e32 v39, 0xffff0000, v30
	v_lshlrev_b32_e32 v40, 16, v31
	v_and_b32_e32 v41, 0xffff0000, v31
	v_mul_f32_e32 v42, v33, v16
	v_mul_f32_e32 v43, v33, v17
	v_mul_f32_e32 v44, v33, v18
	v_mul_f32_e32 v45, v33, v19
	v_mul_f32_e32 v46, v33, v12
	v_mul_f32_e32 v47, v33, v13
	v_mul_f32_e32 v48, v33, v14
	v_mul_f32_e32 v49, v33, v15
	v_mul_f32_e32 v42, v42, v34
	v_mul_f32_e32 v43, v43, v35
	v_mul_f32_e32 v44, v44, v36
	v_mul_f32_e32 v45, v45, v37
	v_mul_f32_e32 v46, v46, v38
	v_mul_f32_e32 v47, v47, v39
	v_mul_f32_e32 v48, v48, v40
	v_mul_f32_e32 v49, v49, v41
	v_cvt_pk_bf16_f32 v54, v42, v43
	v_cvt_pk_bf16_f32 v55, v44, v45
	v_cvt_pk_bf16_f32 v56, v46, v47
	v_cvt_pk_bf16_f32 v57, v48, v49
	global_store_dwordx4 v3, v[54:57], s[98:99]
	v_readlane_b32 s2, v249, 0
	v_readlane_b32 s84, v246, 28
	v_readlane_b32 s1, v246, 25
	s_add_i32 s84, s84, s2
	s_add_i32 s1, s1, s2
	s_cmpk_gt_i32 s84, 0x1ff
	v_readlane_b32 s3, v249, 1
	v_writelane_b32 v246, s1, 25
	s_cbranch_scc0 .LBB0_484
	v_readlane_b32 s84, v249, 7
	v_readlane_b32 s86, v249, 9
	v_readlane_b32 s92, v249, 14
	v_readlane_b32 s80, v249, 5
	v_readlane_b32 s85, v249, 8
	v_readlane_b32 s87, v249, 10
	v_readlane_b32 s88, v249, 11
	v_readlane_b32 s90, v249, 12
	v_readlane_b32 s89, v249, 13
	v_readlane_b32 s93, v249, 15
	v_readlane_b32 s81, v249, 6
